# attention item epilogue: all 16 sub-layer-norm weight slices requested up front, the 16 output stores issue back to back (no per-slice load+store drain)
# baseline (speedup 1.0000x reference)
; DI void attn_item(const Params& p, const int item) {
;     ...
;   __syncthreads();
;   if (c == 0) {
;     float ss = 0.f;
; #pragma unroll
;     for (int db = 0; db < 4; ++db)
; #pragma unroll
;       for (int i = 0; i < 16; ++i) { const float o = O[db][i] * sc - ex[(qs * 128 + 32 * db + (i & 3) + 8 * (i >> 2) + 4 * hl) * 32 + r]; O[db][i] = o; ss += o * o; }
;     ss += __shfl_xor(ss, 32);
;     const float rstd = rsqrtf(ss * (1.f / 128.f) + EPSN) * 0.8f;
;     bf16_t* dst = (bf16_t*)(p.ws + WS_OCAT) + (size_t)(T0 + qpos) * 1024 + h * 128;
; #pragma unroll
;     for (int db = 0; db < 4; ++db)
; #pragma unroll
;       for (int i4 = 0; i4 < 4; ++i4) {
;         const int d0 = 32 * db + 8 * i4 + 4 * hl;
;         const float4 w = *(const float4*)(p.diff_subln_w + d0);
.LBB0_997:
	s_andn2_b64 vcc, exec, s[0:1]
	s_waitcnt vmcnt(0) lgkmcnt(0)
	s_barrier
	s_cbranch_vccnz .LBB0_999
	s_lshl_b32 s0, s14, 14
	v_add3_u32 v66, v65, v64, s0
	v_add_u32_e32 v64, 0x400, v66
	ds_read2_b32 v[72:73], v66 offset1:32
	ds_read2_b32 v[74:75], v66 offset0:64 offset1:96
	ds_read2_b32 v[76:77], v64 offset1:32
	ds_read2_b32 v[78:79], v64 offset0:64 offset1:96
	v_add_u32_e32 v64, 0x800, v66
	ds_read2_b32 v[80:81], v64 offset1:32
	ds_read2_b32 v[82:83], v64 offset0:64 offset1:96
	v_add_u32_e32 v64, 0xc00, v66
	ds_read2_b32 v[84:85], v64 offset1:32
	ds_read2_b32 v[86:87], v64 offset0:64 offset1:96
	v_add_u32_e32 v64, 0x1000, v66
	ds_read2_b32 v[88:89], v64 offset1:32
	ds_read2_b32 v[90:91], v64 offset0:64 offset1:96
	v_add_u32_e32 v64, 0x1400, v66
	ds_read2_b32 v[92:93], v64 offset1:32
	ds_read2_b32 v[94:95], v64 offset0:64 offset1:96
	v_add_u32_e32 v64, 0x1800, v66
	ds_read2_b32 v[96:97], v64 offset1:32
	ds_read2_b32 v[98:99], v64 offset0:64 offset1:96
	v_add_u32_e32 v64, 0x1c00, v66
	ds_read2_b32 v[100:101], v64 offset1:32
	ds_read2_b32 v[102:103], v64 offset0:64 offset1:96
	v_add_u32_e32 v64, 0x2000, v66
	ds_read2_b32 v[104:105], v64 offset1:32
	ds_read2_b32 v[106:107], v64 offset0:64 offset1:96
	v_add_u32_e32 v64, 0x2400, v66
	ds_read2_b32 v[108:109], v64 offset1:32
	ds_read2_b32 v[110:111], v64 offset0:64 offset1:96
	v_add_u32_e32 v64, 0x2800, v66
	ds_read2_b32 v[112:113], v64 offset1:32
	ds_read2_b32 v[114:115], v64 offset0:64 offset1:96
	v_add_u32_e32 v64, 0x2c00, v66
	ds_read2_b32 v[116:117], v64 offset1:32
	ds_read2_b32 v[118:119], v64 offset0:64 offset1:96
	v_add_u32_e32 v64, 0x3000, v66
	ds_read2_b32 v[120:121], v64 offset1:32
	ds_read2_b32 v[122:123], v64 offset0:64 offset1:96
	v_add_u32_e32 v64, 0x3400, v66
	v_add_u32_e32 v67, 0x3c00, v66
	ds_read2_b32 v[124:125], v64 offset1:32
	ds_read2_b32 v[126:127], v64 offset0:64 offset1:96
	ds_read2_b32 v[64:65], v67 offset1:32
	v_add_u32_e32 v70, 0x3800, v66
	ds_read2_b32 v[66:67], v67 offset0:64 offset1:96
	ds_read2_b32 v[128:129], v70 offset1:32
	ds_read2_b32 v[130:131], v70 offset0:64 offset1:96
	s_waitcnt lgkmcnt(14)
	v_pk_fma_f32 v[136:137], v[48:49], v[68:69], v[72:73] op_sel_hi:[1,0,1] neg_lo:[0,0,1] neg_hi:[0,0,1]
	v_pk_fma_f32 v[50:51], v[50:51], v[68:69], v[74:75] op_sel_hi:[1,0,1] neg_lo:[0,0,1] neg_hi:[0,0,1]
	v_pk_mul_f32 v[138:139], v[136:137], v[136:137]
	s_waitcnt lgkmcnt(3)
	v_pk_fma_f32 v[64:65], v[12:13], v[68:69], v[64:65] op_sel_hi:[1,0,1] neg_lo:[0,0,1] neg_hi:[0,0,1]
	s_waitcnt lgkmcnt(2)
	v_pk_fma_f32 v[66:67], v[14:15], v[68:69], v[66:67] op_sel_hi:[1,0,1] neg_lo:[0,0,1] neg_hi:[0,0,1]
	v_pk_mul_f32 v[74:75], v[50:51], v[50:51]
	global_load_dwordx4 v[12:15], v192, s[72:73]
	global_load_dwordx4 v[148:151], v192, s[72:73] offset:32
	global_load_dwordx4 v[152:155], v192, s[72:73] offset:64
	global_load_dwordx4 v[156:159], v192, s[72:73] offset:96
	global_load_dwordx4 v[160:163], v192, s[72:73] offset:128
	global_load_dwordx4 v[164:167], v192, s[72:73] offset:160
	global_load_dwordx4 v[168:171], v192, s[72:73] offset:192
	global_load_dwordx4 v[172:175], v192, s[72:73] offset:224
	global_load_dwordx4 v[176:179], v192, s[72:73] offset:256
	global_load_dwordx4 v[180:183], v192, s[72:73] offset:288
	global_load_dwordx4 v[184:187], v192, s[72:73] offset:320
	global_load_dwordx4 v[188:191], v192, s[72:73] offset:352
	global_load_dwordx4 v[220:223], v192, s[72:73] offset:384
	global_load_dwordx4 v[224:227], v192, s[72:73] offset:416
	global_load_dwordx4 v[228:231], v192, s[72:73] offset:448
	global_load_dwordx4 v[232:235], v192, s[72:73] offset:480
	v_pk_fma_f32 v[72:73], v[54:55], v[68:69], v[78:79] op_sel_hi:[1,0,1] neg_lo:[0,0,1] neg_hi:[0,0,1]
	v_pk_fma_f32 v[76:77], v[52:53], v[68:69], v[76:77] op_sel_hi:[1,0,1] neg_lo:[0,0,1] neg_hi:[0,0,1]
	v_pk_fma_f32 v[58:59], v[58:59], v[68:69], v[82:83] op_sel_hi:[1,0,1] neg_lo:[0,0,1] neg_hi:[0,0,1]
	v_pk_fma_f32 v[80:81], v[56:57], v[68:69], v[80:81] op_sel_hi:[1,0,1] neg_lo:[0,0,1] neg_hi:[0,0,1]
	v_pk_fma_f32 v[54:55], v[62:63], v[68:69], v[86:87] op_sel_hi:[1,0,1] neg_lo:[0,0,1] neg_hi:[0,0,1]
	v_pk_fma_f32 v[84:85], v[60:61], v[68:69], v[84:85] op_sel_hi:[1,0,1] neg_lo:[0,0,1] neg_hi:[0,0,1]
	v_pk_fma_f32 v[52:53], v[34:35], v[68:69], v[90:91] op_sel_hi:[1,0,1] neg_lo:[0,0,1] neg_hi:[0,0,1]
	v_pk_fma_f32 v[88:89], v[32:33], v[68:69], v[88:89] op_sel_hi:[1,0,1] neg_lo:[0,0,1] neg_hi:[0,0,1]
	v_pk_fma_f32 v[48:49], v[38:39], v[68:69], v[94:95] op_sel_hi:[1,0,1] neg_lo:[0,0,1] neg_hi:[0,0,1]
	v_pk_fma_f32 v[60:61], v[36:37], v[68:69], v[92:93] op_sel_hi:[1,0,1] neg_lo:[0,0,1] neg_hi:[0,0,1]
	v_pk_fma_f32 v[38:39], v[42:43], v[68:69], v[98:99] op_sel_hi:[1,0,1] neg_lo:[0,0,1] neg_hi:[0,0,1]
	v_pk_fma_f32 v[56:57], v[40:41], v[68:69], v[96:97] op_sel_hi:[1,0,1] neg_lo:[0,0,1] neg_hi:[0,0,1]
	v_pk_fma_f32 v[34:35], v[46:47], v[68:69], v[102:103] op_sel_hi:[1,0,1] neg_lo:[0,0,1] neg_hi:[0,0,1]
	v_pk_fma_f32 v[44:45], v[44:45], v[68:69], v[100:101] op_sel_hi:[1,0,1] neg_lo:[0,0,1] neg_hi:[0,0,1]
	v_pk_fma_f32 v[32:33], v[18:19], v[68:69], v[106:107] op_sel_hi:[1,0,1] neg_lo:[0,0,1] neg_hi:[0,0,1]
	v_pk_fma_f32 v[42:43], v[16:17], v[68:69], v[104:105] op_sel_hi:[1,0,1] neg_lo:[0,0,1] neg_hi:[0,0,1]
	v_pk_fma_f32 v[22:23], v[22:23], v[68:69], v[110:111] op_sel_hi:[1,0,1] neg_lo:[0,0,1] neg_hi:[0,0,1]
	v_pk_fma_f32 v[40:41], v[20:21], v[68:69], v[108:109] op_sel_hi:[1,0,1] neg_lo:[0,0,1] neg_hi:[0,0,1]
	v_pk_fma_f32 v[20:21], v[26:27], v[68:69], v[114:115] op_sel_hi:[1,0,1] neg_lo:[0,0,1] neg_hi:[0,0,1]
	v_pk_fma_f32 v[36:37], v[24:25], v[68:69], v[112:113] op_sel_hi:[1,0,1] neg_lo:[0,0,1] neg_hi:[0,0,1]
	v_pk_fma_f32 v[18:19], v[30:31], v[68:69], v[118:119] op_sel_hi:[1,0,1] neg_lo:[0,0,1] neg_hi:[0,0,1]
	v_pk_fma_f32 v[26:27], v[28:29], v[68:69], v[116:117] op_sel_hi:[1,0,1] neg_lo:[0,0,1] neg_hi:[0,0,1]
	v_pk_fma_f32 v[16:17], v[2:3], v[68:69], v[122:123] op_sel_hi:[1,0,1] neg_lo:[0,0,1] neg_hi:[0,0,1]
	v_pk_fma_f32 v[24:25], v[0:1], v[68:69], v[120:121] op_sel_hi:[1,0,1] neg_lo:[0,0,1] neg_hi:[0,0,1]
	v_pk_fma_f32 v[2:3], v[6:7], v[68:69], v[126:127] op_sel_hi:[1,0,1] neg_lo:[0,0,1] neg_hi:[0,0,1]
	v_pk_fma_f32 v[6:7], v[4:5], v[68:69], v[124:125] op_sel_hi:[1,0,1] neg_lo:[0,0,1] neg_hi:[0,0,1]
	s_waitcnt lgkmcnt(0)
; DI void attn_item(const Params& p, const int item) {
;     ...
; #pragma unroll
;     for (int db = 0; db < 4; ++db)
; #pragma unroll
;       for (int i = 0; i < 16; ++i) { const float o = O[db][i] * sc - ex[(qs * 128 + 32 * db + (i & 3) + 8 * (i >> 2) + 4 * hl) * 32 + r]; O[db][i] = o; ss += o * o; }
;     ss += __shfl_xor(ss, 32);
;     const float rstd = rsqrtf(ss * (1.f / 128.f) + EPSN) * 0.8f;
;     bf16_t* dst = (bf16_t*)(p.ws + WS_OCAT) + (size_t)(T0 + qpos) * 1024 + h * 128;
	v_pk_fma_f32 v[0:1], v[10:11], v[68:69], v[130:131] op_sel_hi:[1,0,1] neg_lo:[0,0,1] neg_hi:[0,0,1]
	v_pk_fma_f32 v[4:5], v[8:9], v[68:69], v[128:129] op_sel_hi:[1,0,1] neg_lo:[0,0,1] neg_hi:[0,0,1]
	v_add_f32_e32 v68, v138, v139
	v_add_f32_e32 v68, v68, v74
	v_pk_mul_f32 v[140:141], v[76:77], v[76:77]
	v_add_f32_e32 v68, v68, v75
	v_add_f32_e32 v68, v68, v140
	v_pk_mul_f32 v[78:79], v[72:73], v[72:73]
	v_add_f32_e32 v68, v68, v141
	v_add_f32_e32 v68, v68, v78
	v_pk_mul_f32 v[142:143], v[80:81], v[80:81]
	v_add_f32_e32 v68, v68, v79
	v_add_f32_e32 v68, v68, v142
	v_pk_mul_f32 v[82:83], v[58:59], v[58:59]
	v_add_f32_e32 v68, v68, v143
	v_add_f32_e32 v68, v68, v82
	v_pk_mul_f32 v[86:87], v[84:85], v[84:85]
	v_add_f32_e32 v68, v68, v83
	v_add_f32_e32 v68, v68, v86
	v_pk_mul_f32 v[62:63], v[54:55], v[54:55]
	v_add_f32_e32 v68, v68, v87
	v_add_f32_e32 v62, v68, v62
	v_pk_mul_f32 v[144:145], v[88:89], v[88:89]
	v_add_f32_e32 v62, v62, v63
	v_add_f32_e32 v62, v62, v144
	v_pk_mul_f32 v[90:91], v[52:53], v[52:53]
	v_add_f32_e32 v62, v62, v145
	v_add_f32_e32 v62, v62, v90
	v_pk_mul_f32 v[92:93], v[60:61], v[60:61]
	v_add_f32_e32 v62, v62, v91
	v_add_f32_e32 v62, v62, v92
	v_pk_mul_f32 v[94:95], v[48:49], v[48:49]
	v_add_f32_e32 v62, v62, v93
	v_add_f32_e32 v62, v62, v94
	v_pk_mul_f32 v[96:97], v[56:57], v[56:57]
	v_add_f32_e32 v62, v62, v95
	v_add_f32_e32 v62, v62, v96
	v_pk_mul_f32 v[98:99], v[38:39], v[38:39]
	v_add_f32_e32 v62, v62, v97
	v_add_f32_e32 v62, v62, v98
	v_pk_mul_f32 v[100:101], v[44:45], v[44:45]
	v_add_f32_e32 v62, v62, v99
	v_add_f32_e32 v62, v62, v100
	v_pk_mul_f32 v[46:47], v[34:35], v[34:35]
	v_add_f32_e32 v62, v62, v101
	v_add_f32_e32 v46, v62, v46
	v_pk_mul_f32 v[104:105], v[42:43], v[42:43]
	v_add_f32_e32 v46, v46, v47
	v_add_f32_e32 v46, v46, v104
	v_pk_mul_f32 v[102:103], v[32:33], v[32:33]
	v_add_f32_e32 v46, v46, v105
	v_add_f32_e32 v46, v46, v102
	v_pk_mul_f32 v[108:109], v[40:41], v[40:41]
	v_add_f32_e32 v46, v46, v103
	v_add_f32_e32 v46, v46, v108
	v_pk_mul_f32 v[106:107], v[22:23], v[22:23]
	v_add_f32_e32 v46, v46, v109
	v_add_f32_e32 v46, v46, v106
	v_pk_mul_f32 v[112:113], v[36:37], v[36:37]
	v_add_f32_e32 v46, v46, v107
	v_add_f32_e32 v46, v46, v112
	v_pk_mul_f32 v[110:111], v[20:21], v[20:21]
	v_add_f32_e32 v46, v46, v113
	v_add_f32_e32 v46, v46, v110
	v_pk_mul_f32 v[28:29], v[26:27], v[26:27]
	v_add_f32_e32 v46, v46, v111
	v_add_f32_e32 v28, v46, v28
	v_pk_mul_f32 v[30:31], v[18:19], v[18:19]
	v_add_f32_e32 v28, v28, v29
	v_add_f32_e32 v28, v28, v30
	v_pk_mul_f32 v[116:117], v[24:25], v[24:25]
	v_add_f32_e32 v28, v28, v31
	v_add_f32_e32 v28, v28, v116
	v_pk_mul_f32 v[114:115], v[16:17], v[16:17]
	v_add_f32_e32 v28, v28, v117
	v_add_f32_e32 v28, v28, v114
	v_pk_mul_f32 v[120:121], v[6:7], v[6:7]
	v_add_f32_e32 v28, v28, v115
	v_add_f32_e32 v28, v28, v120
	v_pk_mul_f32 v[118:119], v[2:3], v[2:3]
	v_add_f32_e32 v28, v28, v121
	v_add_f32_e32 v28, v28, v118
	v_pk_mul_f32 v[8:9], v[4:5], v[4:5]
	v_add_f32_e32 v28, v28, v119
	v_add_f32_e32 v8, v28, v8
	v_pk_mul_f32 v[10:11], v[0:1], v[0:1]
	v_add_f32_e32 v8, v8, v9
	v_add_f32_e32 v8, v8, v10
	v_pk_mul_f32 v[70:71], v[64:65], v[64:65]
	v_add_f32_e32 v8, v8, v11
	v_add_f32_e32 v8, v8, v70
	v_pk_mul_f32 v[132:133], v[66:67], v[66:67]
	v_add_f32_e32 v8, v8, v71
	v_add_f32_e32 v8, v8, v132
	v_add_f32_e32 v10, v8, v133
	ds_bpermute_b32 v11, v69, v10
	s_mov_b32 s0, 0x800000
	v_add_u32_e32 v134, s6, v199
	v_mov_b32_e32 v135, v193
	v_lshlrev_b64 v[8:9], 11, v[134:135]
	s_waitcnt lgkmcnt(0)
	v_add_f32_e32 v10, v10, v11
	v_fmamk_f32 v10, v10, 0x3c000000, v212
	v_mul_f32_e32 v11, 0x4b800000, v10
	v_cmp_gt_f32_e32 vcc, s0, v10
	v_lshl_add_u64 v[8:9], s[68:69], 0, v[8:9]
	s_lshl_b32 s70, s3, 8
	v_cndmask_b32_e32 v10, v10, v11, vcc
	v_rsq_f32_e32 v10, v10
	v_lshl_add_u64 v[8:9], v[8:9], 0, s[70:71]
	v_mov_b32_e32 v199, v193
	v_lshl_add_u64 v[28:29], v[8:9], 0, v[198:199]
	v_mul_f32_e32 v8, 0x45800000, v10
	v_cndmask_b32_e32 v8, v10, v8, vcc
	v_mul_f32_e32 v30, 0x3f4ccccd, v8
	s_waitcnt vmcnt(0)
; DI unsigned pk_bf16(float lo, float hi) { f32x2 v = {lo, hi}; return __builtin_bit_cast(unsigned, __builtin_convertvector(v, bf16x2_t)); }
; DI void attn_item(const Params& p, const int item) {
;     ...
;     bf16_t* dst = (bf16_t*)(p.ws + WS_OCAT) + (size_t)(T0 + qpos) * 1024 + h * 128;
; #pragma unroll
;     for (int db = 0; db < 4; ++db)
; #pragma unroll
;       for (int i4 = 0; i4 < 4; ++i4) {
;         const int d0 = 32 * db + 8 * i4 + 4 * hl;
;         const float4 w = *(const float4*)(p.diff_subln_w + d0);
;         uint2 q; q.x = pk_bf16(O[db][4 * i4] * rstd * w.x, O[db][4 * i4 + 1] * rstd * w.y); q.y = pk_bf16(O[db][4 * i4 + 2] * rstd * w.z, O[db][4 * i4 + 3] * rstd * w.w);
;         *(uint2*)(dst + d0) = q;
;       }
	v_pk_mul_f32 v[244:245], v[136:137], v[30:31] op_sel_hi:[1,0]
	v_pk_mul_f32 v[246:247], v[50:51], v[30:31] op_sel_hi:[1,0]
	v_pk_mul_f32 v[244:245], v[12:13], v[244:245]
	v_pk_mul_f32 v[246:247], v[14:15], v[246:247]
	v_cvt_pk_bf16_f32 v248, v244, v245
	v_cvt_pk_bf16_f32 v249, v246, v247
	global_store_dwordx2 v[28:29], v[248:249], off
	v_pk_mul_f32 v[244:245], v[76:77], v[30:31] op_sel_hi:[1,0]
	v_pk_mul_f32 v[246:247], v[72:73], v[30:31] op_sel_hi:[1,0]
	v_pk_mul_f32 v[244:245], v[148:149], v[244:245]
	v_pk_mul_f32 v[246:247], v[150:151], v[246:247]
	v_cvt_pk_bf16_f32 v250, v244, v245
	v_cvt_pk_bf16_f32 v251, v246, v247
	global_store_dwordx2 v[28:29], v[250:251], off offset:16
	v_pk_mul_f32 v[244:245], v[80:81], v[30:31] op_sel_hi:[1,0]
	v_pk_mul_f32 v[246:247], v[58:59], v[30:31] op_sel_hi:[1,0]
	v_pk_mul_f32 v[244:245], v[152:153], v[244:245]
	v_pk_mul_f32 v[246:247], v[154:155], v[246:247]
	v_cvt_pk_bf16_f32 v248, v244, v245
	v_cvt_pk_bf16_f32 v249, v246, v247
	global_store_dwordx2 v[28:29], v[248:249], off offset:32
	v_pk_mul_f32 v[244:245], v[84:85], v[30:31] op_sel_hi:[1,0]
	v_pk_mul_f32 v[246:247], v[54:55], v[30:31] op_sel_hi:[1,0]
	v_pk_mul_f32 v[244:245], v[156:157], v[244:245]
	v_pk_mul_f32 v[246:247], v[158:159], v[246:247]
	v_cvt_pk_bf16_f32 v250, v244, v245
	v_cvt_pk_bf16_f32 v251, v246, v247
	global_store_dwordx2 v[28:29], v[250:251], off offset:48
	v_pk_mul_f32 v[244:245], v[88:89], v[30:31] op_sel_hi:[1,0]
	v_pk_mul_f32 v[246:247], v[52:53], v[30:31] op_sel_hi:[1,0]
	v_pk_mul_f32 v[244:245], v[160:161], v[244:245]
	v_pk_mul_f32 v[246:247], v[162:163], v[246:247]
	v_cvt_pk_bf16_f32 v248, v244, v245
	v_cvt_pk_bf16_f32 v249, v246, v247
	global_store_dwordx2 v[28:29], v[248:249], off offset:64
	v_pk_mul_f32 v[244:245], v[60:61], v[30:31] op_sel_hi:[1,0]
	v_pk_mul_f32 v[246:247], v[48:49], v[30:31] op_sel_hi:[1,0]
	v_pk_mul_f32 v[244:245], v[164:165], v[244:245]
	v_pk_mul_f32 v[246:247], v[166:167], v[246:247]
	v_cvt_pk_bf16_f32 v250, v244, v245
	v_cvt_pk_bf16_f32 v251, v246, v247
	global_store_dwordx2 v[28:29], v[250:251], off offset:80
	v_pk_mul_f32 v[244:245], v[56:57], v[30:31] op_sel_hi:[1,0]
	v_pk_mul_f32 v[246:247], v[38:39], v[30:31] op_sel_hi:[1,0]
	v_pk_mul_f32 v[244:245], v[168:169], v[244:245]
	v_pk_mul_f32 v[246:247], v[170:171], v[246:247]
	v_cvt_pk_bf16_f32 v248, v244, v245
	v_cvt_pk_bf16_f32 v249, v246, v247
	global_store_dwordx2 v[28:29], v[248:249], off offset:96
	v_pk_mul_f32 v[244:245], v[44:45], v[30:31] op_sel_hi:[1,0]
	v_pk_mul_f32 v[246:247], v[34:35], v[30:31] op_sel_hi:[1,0]
	v_pk_mul_f32 v[244:245], v[172:173], v[244:245]
	v_pk_mul_f32 v[246:247], v[174:175], v[246:247]
	v_cvt_pk_bf16_f32 v250, v244, v245
	v_cvt_pk_bf16_f32 v251, v246, v247
	global_store_dwordx2 v[28:29], v[250:251], off offset:112
	v_pk_mul_f32 v[244:245], v[42:43], v[30:31] op_sel_hi:[1,0]
	v_pk_mul_f32 v[246:247], v[32:33], v[30:31] op_sel_hi:[1,0]
	v_pk_mul_f32 v[244:245], v[176:177], v[244:245]
	v_pk_mul_f32 v[246:247], v[178:179], v[246:247]
	v_cvt_pk_bf16_f32 v248, v244, v245
	v_cvt_pk_bf16_f32 v249, v246, v247
	global_store_dwordx2 v[28:29], v[248:249], off offset:128
	v_pk_mul_f32 v[244:245], v[40:41], v[30:31] op_sel_hi:[1,0]
	v_pk_mul_f32 v[246:247], v[22:23], v[30:31] op_sel_hi:[1,0]
	v_pk_mul_f32 v[244:245], v[180:181], v[244:245]
	v_pk_mul_f32 v[246:247], v[182:183], v[246:247]
	v_cvt_pk_bf16_f32 v250, v244, v245
	v_cvt_pk_bf16_f32 v251, v246, v247
	global_store_dwordx2 v[28:29], v[250:251], off offset:144
	v_pk_mul_f32 v[244:245], v[36:37], v[30:31] op_sel_hi:[1,0]
	v_pk_mul_f32 v[246:247], v[20:21], v[30:31] op_sel_hi:[1,0]
	v_pk_mul_f32 v[244:245], v[184:185], v[244:245]
	v_pk_mul_f32 v[246:247], v[186:187], v[246:247]
	v_cvt_pk_bf16_f32 v248, v244, v245
	v_cvt_pk_bf16_f32 v249, v246, v247
	global_store_dwordx2 v[28:29], v[248:249], off offset:160
	v_pk_mul_f32 v[244:245], v[26:27], v[30:31] op_sel_hi:[1,0]
	v_pk_mul_f32 v[246:247], v[18:19], v[30:31] op_sel_hi:[1,0]
	v_pk_mul_f32 v[244:245], v[188:189], v[244:245]
	v_pk_mul_f32 v[246:247], v[190:191], v[246:247]
	v_cvt_pk_bf16_f32 v250, v244, v245
	v_cvt_pk_bf16_f32 v251, v246, v247
	global_store_dwordx2 v[28:29], v[250:251], off offset:176
	v_pk_mul_f32 v[244:245], v[24:25], v[30:31] op_sel_hi:[1,0]
	v_pk_mul_f32 v[246:247], v[16:17], v[30:31] op_sel_hi:[1,0]
	v_pk_mul_f32 v[244:245], v[220:221], v[244:245]
	v_pk_mul_f32 v[246:247], v[222:223], v[246:247]
	v_cvt_pk_bf16_f32 v248, v244, v245
	v_cvt_pk_bf16_f32 v249, v246, v247
	global_store_dwordx2 v[28:29], v[248:249], off offset:192
	v_pk_mul_f32 v[244:245], v[6:7], v[30:31] op_sel_hi:[1,0]
	v_pk_mul_f32 v[246:247], v[2:3], v[30:31] op_sel_hi:[1,0]
	v_pk_mul_f32 v[244:245], v[224:225], v[244:245]
	v_pk_mul_f32 v[246:247], v[226:227], v[246:247]
	v_cvt_pk_bf16_f32 v250, v244, v245
	v_cvt_pk_bf16_f32 v251, v246, v247
	global_store_dwordx2 v[28:29], v[250:251], off offset:208
	v_pk_mul_f32 v[244:245], v[4:5], v[30:31] op_sel_hi:[1,0]
	v_pk_mul_f32 v[246:247], v[0:1], v[30:31] op_sel_hi:[1,0]
	v_pk_mul_f32 v[244:245], v[228:229], v[244:245]
	v_pk_mul_f32 v[246:247], v[230:231], v[246:247]
	v_cvt_pk_bf16_f32 v248, v244, v245
	v_cvt_pk_bf16_f32 v249, v246, v247
	global_store_dwordx2 v[28:29], v[248:249], off offset:224
	v_pk_mul_f32 v[244:245], v[64:65], v[30:31] op_sel_hi:[1,0]
	v_pk_mul_f32 v[246:247], v[66:67], v[30:31] op_sel_hi:[1,0]
	v_pk_mul_f32 v[244:245], v[232:233], v[244:245]
	v_pk_mul_f32 v[246:247], v[234:235], v[246:247]
	v_cvt_pk_bf16_f32 v250, v244, v245
	v_cvt_pk_bf16_f32 v251, v246, v247
	global_store_dwordx2 v[28:29], v[250:251], off offset:240
